# top-k bisection counting via v_med3_u32 + v_add3_u32 (1.5 VALU per key instead of 2), on top of the XCC-hierarchical grid barrier
# speedup vs baseline: 1.0222x; 1.0077x over previous
; #define PAIR_XCHG(SLOT, TAG, MINE, OTHER) do { const unsigned tg_ = (seq << 8) | (unsigned)(TAG); if (lane == 0) xw[w * 4 + (SLOT)] = ((MINE) << 16) | tg_; \
;             unsigned v_; do { v_ = xw[(w ^ 1) * 4 + (SLOT)]; } while ((v_ & 0xffffu) != tg_); OTHER = v_ >> 16; } while (0)
; __device__ __forceinline__ void attn_item(const Ptrs& P, unsigned char* lds, int b, int tq0, int tid) {
;     ...
;             const unsigned cand = th | (1u << bit); unsigned cnt = 0, oth;
; #pragma unroll
;             for (int k = 0; k < 4; ++k) if (16 * k < nact) {
; #pragma unroll
;                 for (int r = 16 * k; r < 16 * k + 16; ++r) cnt += (unsigned)__popcll(__ballot(k2[r] >= cand)); }
;             PAIR_XCHG(bit & 1, 1 + bit, cnt, oth);
;             cnt += oth;
;             if (cnt >= 256u) th = cand;
;             if (cnt == 256u) break;
;         }
.Lbis_loop:
	s_lshl_b32 s12, 1, s75
	s_or_b32 s12, s85, s12
	s_lshr_b32 s13, s12, 16
	s_cmp_gt_u32 s13, s84
	s_cbranch_scc1 .Lbis_next
	v_mov_b32_e32 v24, s12
	v_mov_b32_e32 v25, 0
	v_add_u32_e32 v26, -1, v24
	s_mov_b32 s90, 0
	s_cmp_eq_u64 s[18:19], 0
	s_cbranch_scc1 .Lbis_cnt_done
	v_med3_u32 v38, v6, v26, v24
	v_med3_u32 v39, v95, v26, v24
	v_add3_u32 v25, v25, v38, v39
	v_med3_u32 v40, v94, v26, v24
	v_med3_u32 v41, v93, v26, v24
	v_add3_u32 v25, v25, v40, v41
	v_med3_u32 v42, v92, v26, v24
	v_med3_u32 v43, v91, v26, v24
	v_add3_u32 v25, v25, v42, v43
	v_med3_u32 v44, v90, v26, v24
	v_med3_u32 v45, v89, v26, v24
	v_add3_u32 v25, v25, v44, v45
	v_med3_u32 v38, v88, v26, v24
	v_med3_u32 v39, v87, v26, v24
	v_add3_u32 v25, v25, v38, v39
	v_med3_u32 v40, v86, v26, v24
	v_med3_u32 v41, v85, v26, v24
	v_add3_u32 v25, v25, v40, v41
	v_med3_u32 v42, v84, v26, v24
	v_med3_u32 v43, v83, v26, v24
	v_add3_u32 v25, v25, v42, v43
	v_med3_u32 v44, v82, v26, v24
	v_med3_u32 v45, v81, v26, v24
	v_add3_u32 v25, v25, v44, v45
	s_mov_b32 s90, 16
	s_cmp_eq_u64 s[16:17], 0
	s_cbranch_scc1 .Lbis_cnt_done
	v_med3_u32 v38, v4, v26, v24
	v_med3_u32 v39, v80, v26, v24
	v_add3_u32 v25, v25, v38, v39
	v_med3_u32 v40, v79, v26, v24
	v_med3_u32 v41, v78, v26, v24
	v_add3_u32 v25, v25, v40, v41
	v_med3_u32 v42, v77, v26, v24
	v_med3_u32 v43, v76, v26, v24
	v_add3_u32 v25, v25, v42, v43
	v_med3_u32 v44, v75, v26, v24
	v_med3_u32 v45, v74, v26, v24
	v_add3_u32 v25, v25, v44, v45
	v_med3_u32 v38, v73, v26, v24
	v_med3_u32 v39, v72, v26, v24
	v_add3_u32 v25, v25, v38, v39
	v_med3_u32 v40, v71, v26, v24
	v_med3_u32 v41, v70, v26, v24
	v_add3_u32 v25, v25, v40, v41
	v_med3_u32 v42, v69, v26, v24
	v_med3_u32 v43, v68, v26, v24
	v_add3_u32 v25, v25, v42, v43
	v_med3_u32 v44, v67, v26, v24
	v_med3_u32 v45, v66, v26, v24
	v_add3_u32 v25, v25, v44, v45
	s_mov_b32 s90, 32
	s_cmp_eq_u64 s[14:15], 0
	s_cbranch_scc1 .Lbis_cnt_done
	v_med3_u32 v38, v2, v26, v24
	v_med3_u32 v39, v65, v26, v24
	v_add3_u32 v25, v25, v38, v39
	v_med3_u32 v40, v64, v26, v24
	v_med3_u32 v41, v49, v26, v24
	v_add3_u32 v25, v25, v40, v41
	v_med3_u32 v42, v48, v26, v24
	v_med3_u32 v43, v46, v26, v24
	v_add3_u32 v25, v25, v42, v43
	v_med3_u32 v44, v35, v26, v24
	v_med3_u32 v45, v34, v26, v24
	v_add3_u32 v25, v25, v44, v45
	v_med3_u32 v38, v33, v26, v24
	v_med3_u32 v39, v32, v26, v24
	v_add3_u32 v25, v25, v38, v39
	v_med3_u32 v40, v31, v26, v24
	v_med3_u32 v41, v30, v26, v24
	v_add3_u32 v25, v25, v40, v41
	v_med3_u32 v42, v28, v26, v24
	v_med3_u32 v43, v23, v26, v24
	v_add3_u32 v25, v25, v42, v43
	v_med3_u32 v44, v22, v26, v24
	v_med3_u32 v45, v21, v26, v24
	v_add3_u32 v25, v25, v44, v45
	s_mov_b32 s90, 48
	s_cmp_eq_u64 vcc, 0
	s_cbranch_scc1 .Lbis_cnt_done
	v_med3_u32 v38, v0, v26, v24
	v_med3_u32 v39, v20, v26, v24
	v_add3_u32 v25, v25, v38, v39
	v_med3_u32 v40, v19, v26, v24
	v_med3_u32 v41, v18, v26, v24
	v_add3_u32 v25, v25, v40, v41
	v_med3_u32 v42, v17, v26, v24
	v_med3_u32 v43, v16, v26, v24
	v_add3_u32 v25, v25, v42, v43
	v_med3_u32 v44, v15, v26, v24
	v_med3_u32 v45, v14, v26, v24
	v_add3_u32 v25, v25, v44, v45
	v_med3_u32 v38, v13, v26, v24
	v_med3_u32 v39, v12, v26, v24
	v_add3_u32 v25, v25, v38, v39
	v_med3_u32 v40, v11, v26, v24
	v_med3_u32 v41, v10, v26, v24
	v_add3_u32 v25, v25, v40, v41
	v_med3_u32 v42, v9, v26, v24
	v_med3_u32 v43, v8, v26, v24
	v_add3_u32 v25, v25, v42, v43
	v_med3_u32 v44, v7, v26, v24
	v_med3_u32 v45, v3, v26, v24
	v_add3_u32 v25, v25, v44, v45
	s_mov_b32 s90, 64
.Lbis_cnt_done:
	s_sub_u32 s91, s12, 1
	s_mul_i32 s91, s91, s90
	v_subrev_u32_e32 v25, s91, v25
	s_add_i32 s13, s75, 1
	s_or_b32 s13, s86, s13
	v_add_u32_dpp v25, v25, v25 row_ror:1 row_mask:0xf bank_mask:0xf
	s_nop 1
	v_add_u32_dpp v25, v25, v25 row_ror:2 row_mask:0xf bank_mask:0xf
	s_nop 1
	v_add_u32_dpp v25, v25, v25 row_ror:4 row_mask:0xf bank_mask:0xf
	s_nop 1
	v_add_u32_dpp v25, v25, v25 row_ror:8 row_mask:0xf bank_mask:0xf
	v_mov_b32_e32 v36, s87
	v_mov_b32_e32 v37, s88
	v_readlane_b32 s78, v25, 0
	v_readlane_b32 s79, v25, 16
	v_readlane_b32 s90, v25, 32
	v_readlane_b32 s91, v25, 48
	s_mov_b64 s[44:45], exec
	s_nop 2
	s_add_i32 s78, s78, s79
	s_add_i32 s90, s90, s91
	s_add_i32 s78, s78, s90
	s_lshl_b32 s20, s78, 16
	s_or_b32 s20, s20, s13
	v_mov_b32_e32 v27, s20
	s_mov_b64 exec, s[4:5]
	ds_write_b32 v36, v27
	s_mov_b64 exec, s[44:45]

; #define PAIR_XCHG(SLOT, TAG, MINE, OTHER) do { const unsigned tg_ = (seq << 8) | (unsigned)(TAG); if (lane == 0) xw[w * 4 + (SLOT)] = ((MINE) << 16) | tg_; \
;             unsigned v_; do { v_ = xw[(w ^ 1) * 4 + (SLOT)]; } while ((v_ & 0xffffu) != tg_); OTHER = v_ >> 16; } while (0)
; __device__ __forceinline__ void attn_item(const Ptrs& P, unsigned char* lds, int b, int tq0, int tid) {
;     ...
;             const unsigned cand = th | (1u << bit); unsigned cnt = 0, oth;
; #pragma unroll
;             for (int k = 0; k < 4; ++k) if (16 * k < nact) {
; #pragma unroll
;                 for (int r = 16 * k; r < 16 * k + 16; ++r) cnt += (unsigned)__popcll(__ballot(k2[r] >= cand)); }
;             PAIR_XCHG(bit & 1, 1 + bit, cnt, oth);
;             cnt += oth;
;             if (cnt >= 256u) th = cand;
;             if (cnt == 256u) break;
;         }
.Lbis_next:
	s_cmp_eq_u32 s75, 0
	s_cbranch_scc1 .Lbis_done
	s_sub_i32 s75, s75, 1
	s_branch .Lbis_loop
	s_nop 0
	s_nop 0
	s_nop 0
	s_nop 0
	s_nop 0
	s_nop 0
	s_nop 0
